# in-proj GEMM: per-iteration stage-pointer selection rotated out of the head of the first load segment to the end of the previous iteration
# speedup vs baseline: 1.0042x; 1.0042x over previous
; #define PG8_STAGE(bufoff, gbase, voff) do { _Pragma("unroll") for (int _i = 0; _i < 2; ++_i) \
;         __builtin_amdgcn_global_load_lds((const unsigned*)((const char*)(gbase) + (voff)[_i]), (LAS unsigned*)(lds + (bufoff) + ldsw + _i * 8192), 16, 0, 0); } while (0)
; #define PG8_LDA(dst, b, h) do { _Pragma("unroll") for (int m = 0; m < 4; ++m) _Pragma("unroll") for (int k = 0; k < 2; ++k) dst[m][k] = *(const LAS bf16x8*)(lds + PG8_SA(b, h) + aoff + m * 2048 + k * 1024); } while (0)
; #define PG8_LDB(dst, b, h) do { _Pragma("unroll") for (int n = 0; n < 2; ++n) _Pragma("unroll") for (int k = 0; k < 2; ++k) dst[n][k] = *(const LAS bf16x8*)(lds + PG8_SB(b, h) + boff + n * 2048 + k * 1024); } while (0)
; #define PG8_MMA(ai, bj, At, Bt) do { __builtin_amdgcn_s_setprio(1); _Pragma("unroll") for (int m = 0; m < 4; ++m) _Pragma("unroll") for (int n = 0; n < 2; ++n) _Pragma("unroll") for (int k = 0; k < 2; ++k) \
;         acc[ai][bj][m][n] = __builtin_amdgcn_mfma_f32_16x16x32_bf16(Bt[n][k], At[m][k], acc[ai][bj][m][n], 0, 0, 0); __builtin_amdgcn_s_setprio(0); } while (0)
; #define PG8_WAIT_L(n) asm volatile("s_waitcnt lgkmcnt(" #n ")" ::: "memory")
; template <class Epi>
; DI void gemm_phase(LAS unsigned char* lds, const Gemm g, const StaticOrder& S, const Epi& E, const int tid) {
;     ...
;         const bool has_next = S.next(ui + 1, nxt);
;         const char* nA = has_next ? (const char*)g.A + (size_t)nxt.pm * tstepA : cA; const char* nB = has_next ? (const char*)g.Bt + (size_t)nxt.pn * tstepB : cB;
;         for (int t = 0; t < nt; t += 2) {
;             const bool last = (t == nt - 2);
;             const char* a1 = cA + PG8_KTA(t + 1);
;             const char* a2 = last ? nA : cA + PG8_KTA(t + 2); const char* b2 = last ? nB : cB + (size_t)(t + 2) * kstep;
;             const char* a3 = last ? nA + PG8_KTA(1) : cA + PG8_KTA(t + 3); const char* b3 = b2 + kstep;
;             PG8_LDB(B0, 0, 0); PG8_SCHED; PG8_LDA(At, 0, 0); PG8_STAGE(PG8_SA(1, 1), a1 + hstepA, voffA);
;             PG8_WAIT_L(8); PG8_BAR; PG8_WAIT_L(0); PG8_MMA(0, 0, At, B0); PG8_BAR; PG8_SCHED;
;     ...
;         for (int a = 0; a < 2; ++a)
; #pragma unroll
;             for (int b = 0; b < 2; ++b)
; #pragma unroll
;                 for (int m = 0; m < 4; ++m)
; #pragma unroll
;                     for (int n = 0; n < 2; ++n) acc[a][b][m][n] = (f32x4){0.f, 0.f, 0.f, 0.f};
.LBB0_61:
	s_ashr_i32 s43, s42, 31
	v_cmp_lt_i64_e32 vcc, s[6:7], v[142:143]
	s_lshl_b64 s[6:7], s[42:43], 20
	s_add_u32 s46, s70, s6
	s_addc_u32 s47, s71, s7
	s_and_b64 s[6:7], vcc, exec
	s_cselect_b32 s30, s47, s45
	s_cselect_b32 s31, s46, s44
	s_ashr_i32 s39, s38, 31
	s_lshl_b64 s[6:7], s[38:39], 20
	s_add_u32 s48, s36, s6
	s_addc_u32 s49, s37, s7
	s_and_b64 s[6:7], vcc, exec
	s_cselect_b32 s39, s49, s5
	s_cselect_b32 s43, s48, s4
	s_add_u32 s64, s31, 0x80
	s_addc_u32 s65, s30, 0
	s_add_u32 s6, s44, 0x80080
	s_addc_u32 s7, s45, 0
	s_add_u32 s66, s4, 0x100
	v_mov_b32_e32 v2, 0
	s_addc_u32 s67, s5, 0
	s_mov_b32 s68, -2
	s_mov_b64 s[4:5], 0
	v_mov_b32_e32 v3, v2
	v_mov_b32_e32 v4, v2
	v_mov_b32_e32 v5, v2
	v_mov_b32_e32 v6, v2
	v_mov_b32_e32 v7, v2
	v_mov_b32_e32 v8, v2
	v_mov_b32_e32 v9, v2
	v_mov_b32_e32 v10, v2
	v_mov_b32_e32 v11, v2
	v_mov_b32_e32 v12, v2
	v_mov_b32_e32 v13, v2
	v_mov_b32_e32 v14, v2
	v_mov_b32_e32 v15, v2
	v_mov_b32_e32 v16, v2
	v_mov_b32_e32 v17, v2
	v_mov_b32_e32 v26, v2
	v_mov_b32_e32 v27, v2
	v_mov_b32_e32 v28, v2
	v_mov_b32_e32 v29, v2
	v_mov_b32_e32 v30, v2
	v_mov_b32_e32 v31, v2
	v_mov_b32_e32 v32, v2
	v_mov_b32_e32 v33, v2
	v_mov_b32_e32 v42, v2
	v_mov_b32_e32 v43, v2
	v_mov_b32_e32 v44, v2
	v_mov_b32_e32 v45, v2
	v_mov_b32_e32 v46, v2
	v_mov_b32_e32 v47, v2
	v_mov_b32_e32 v48, v2
	v_mov_b32_e32 v49, v2
	v_mov_b32_e32 v18, v2
	v_mov_b32_e32 v19, v2
	v_mov_b32_e32 v20, v2
	v_mov_b32_e32 v21, v2
	v_mov_b32_e32 v22, v2
	v_mov_b32_e32 v23, v2
	v_mov_b32_e32 v24, v2
	v_mov_b32_e32 v25, v2
	v_mov_b32_e32 v34, v2
	v_mov_b32_e32 v35, v2
	v_mov_b32_e32 v36, v2
	v_mov_b32_e32 v37, v2
	v_mov_b32_e32 v38, v2
	v_mov_b32_e32 v39, v2
	v_mov_b32_e32 v40, v2
	v_mov_b32_e32 v41, v2
	v_mov_b32_e32 v50, v2
	v_mov_b32_e32 v51, v2
	v_mov_b32_e32 v52, v2
	v_mov_b32_e32 v53, v2
	v_mov_b32_e32 v54, v2
	v_mov_b32_e32 v55, v2
	v_mov_b32_e32 v56, v2
	v_mov_b32_e32 v57, v2
	v_mov_b32_e32 v58, v2
	v_mov_b32_e32 v59, v2
	v_mov_b32_e32 v60, v2
	v_mov_b32_e32 v61, v2
	v_mov_b32_e32 v62, v2
	v_mov_b32_e32 v63, v2
	v_mov_b32_e32 v64, v2
	v_mov_b32_e32 v65, v2
	v_mov_b32_e32 v66, v2
	v_mov_b32_e32 v67, v2
	v_mov_b32_e32 v68, v2
	v_mov_b32_e32 v69, v2
	v_mov_b32_e32 v70, v2
	v_mov_b32_e32 v71, v2
	v_mov_b32_e32 v72, v2
	v_mov_b32_e32 v73, v2
	v_mov_b32_e32 v74, v2
	v_mov_b32_e32 v75, v2
	v_mov_b32_e32 v76, v2
	v_mov_b32_e32 v77, v2
	v_mov_b32_e32 v78, v2
	v_mov_b32_e32 v79, v2
	v_mov_b32_e32 v80, v2
	v_mov_b32_e32 v81, v2
	v_mov_b32_e32 v90, v2
	v_mov_b32_e32 v91, v2
	v_mov_b32_e32 v92, v2
	v_mov_b32_e32 v93, v2
	v_mov_b32_e32 v94, v2
	v_mov_b32_e32 v95, v2
	v_mov_b32_e32 v96, v2
	v_mov_b32_e32 v97, v2
	v_mov_b32_e32 v106, v2
	v_mov_b32_e32 v107, v2
	v_mov_b32_e32 v108, v2
	v_mov_b32_e32 v109, v2
	v_mov_b32_e32 v110, v2
	v_mov_b32_e32 v111, v2
	v_mov_b32_e32 v112, v2
	v_mov_b32_e32 v113, v2
	v_mov_b32_e32 v82, v2
	v_mov_b32_e32 v83, v2
	v_mov_b32_e32 v84, v2
	v_mov_b32_e32 v85, v2
	v_mov_b32_e32 v86, v2
	v_mov_b32_e32 v87, v2
	v_mov_b32_e32 v88, v2
	v_mov_b32_e32 v89, v2
	v_mov_b32_e32 v98, v2
	v_mov_b32_e32 v99, v2
	v_mov_b32_e32 v100, v2
	v_mov_b32_e32 v101, v2
	v_mov_b32_e32 v102, v2
	v_mov_b32_e32 v103, v2
	v_mov_b32_e32 v104, v2
	v_mov_b32_e32 v105, v2
	v_mov_b32_e32 v114, v2
	v_mov_b32_e32 v115, v2
	v_mov_b32_e32 v116, v2
	v_mov_b32_e32 v117, v2
	v_mov_b32_e32 v118, v2
	v_mov_b32_e32 v119, v2
	v_mov_b32_e32 v120, v2
	v_mov_b32_e32 v121, v2
	v_mov_b32_e32 v122, v2
	v_mov_b32_e32 v123, v2
	v_mov_b32_e32 v124, v2
	v_mov_b32_e32 v125, v2
	v_mov_b32_e32 v126, v2
	v_mov_b32_e32 v127, v2
	v_mov_b32_e32 v128, v2
	v_mov_b32_e32 v129, v2
	v_lshl_add_u64 v[144:145], s[6:7], 0, v[138:139]
	v_lshl_add_u64 v[146:147], s[6:7], 0, v[140:141]
	s_add_u32 s6, s44, s4
	s_addc_u32 s7, s45, s5
	s_add_u32 s8, s6, 0x100
	s_addc_u32 s9, s7, 0
	s_add_u32 s69, s66, s4
	s_addc_u32 s78, s67, s5
	s_add_u32 s86, s6, 0x180
	s_addc_u32 s87, s7, 0
	s_cmpk_eq_i32 s4, 0xf00
	s_cselect_b32 s51, s30, s9
	s_cselect_b32 s50, s31, s8
	s_cselect_b32 s7, s39, s78
	s_cselect_b32 s6, s43, s69
	s_cselect_b32 s9, s65, s87
	s_cselect_b32 s8, s64, s86
.LBB0_62:
	s_add_i32 s69, 0, 0x10000
	v_add_u32_e32 v152, s69, v150
	ds_read_b128 v[158:161], v152
	ds_read_b128 v[162:165], v152 offset:1024
	ds_read_b128 v[166:169], v152 offset:2048
	ds_read_b128 v[178:181], v152 offset:3072
	v_lshl_add_u64 v[152:153], v[144:145], 0, s[4:5]
	s_add_i32 m0, s41, 0xc000
	ds_read_b128 v[182:185], v151
	ds_read_b128 v[186:189], v151 offset:1024
	ds_read_b128 v[190:193], v151 offset:2048
	ds_read_b128 v[194:197], v151 offset:3072
	ds_read_b128 v[198:201], v151 offset:4096
	ds_read_b128 v[202:205], v151 offset:5120
	ds_read_b128 v[206:209], v151 offset:6144
	ds_read_b128 v[210:213], v151 offset:7168
	global_load_lds_dwordx4 v[152:153], off
	v_lshl_add_u64 v[152:153], v[146:147], 0, s[4:5]
	s_add_i32 m0, s41, 0xe000
	s_nop 0
	global_load_lds_dwordx4 v[152:153], off
	s_waitcnt lgkmcnt(8)
	s_barrier
	s_waitcnt lgkmcnt(0)
	s_setprio 1
	s_waitcnt lgkmcnt(0)
	v_mfma_f32_16x16x32_bf16 v[126:129], v[158:161], v[182:185], v[126:129]
	v_mfma_f32_16x16x32_bf16 v[122:125], v[166:169], v[182:185], v[122:125]
	v_mfma_f32_16x16x32_bf16 v[118:121], v[158:161], v[190:193], v[118:121]
	v_mfma_f32_16x16x32_bf16 v[114:117], v[166:169], v[190:193], v[114:117]
	v_mfma_f32_16x16x32_bf16 v[102:105], v[158:161], v[198:201], v[102:105]
	v_mfma_f32_16x16x32_bf16 v[98:101], v[166:169], v[198:201], v[98:101]
	v_mfma_f32_16x16x32_bf16 v[86:89], v[158:161], v[206:209], v[86:89]
	v_mfma_f32_16x16x32_bf16 v[82:85], v[166:169], v[206:209], v[82:85]
	v_mfma_f32_16x16x32_bf16 v[126:129], v[162:165], v[186:189], v[126:129]
	v_mfma_f32_16x16x32_bf16 v[122:125], v[178:181], v[186:189], v[122:125]
	v_mfma_f32_16x16x32_bf16 v[118:121], v[162:165], v[194:197], v[118:121]
	v_mfma_f32_16x16x32_bf16 v[114:117], v[178:181], v[194:197], v[114:117]
	v_mfma_f32_16x16x32_bf16 v[102:105], v[162:165], v[202:205], v[102:105]
	v_mfma_f32_16x16x32_bf16 v[98:101], v[178:181], v[202:205], v[98:101]
	v_mfma_f32_16x16x32_bf16 v[86:89], v[162:165], v[210:213], v[86:89]
	v_mfma_f32_16x16x32_bf16 v[82:85], v[178:181], v[210:213], v[82:85]
	s_setprio 0
	s_barrier
; #define PG8_STAGE(bufoff, gbase, voff) do { _Pragma("unroll") for (int _i = 0; _i < 2; ++_i) \
;         __builtin_amdgcn_global_load_lds((const unsigned*)((const char*)(gbase) + (voff)[_i]), (LAS unsigned*)(lds + (bufoff) + ldsw + _i * 8192), 16, 0, 0); } while (0)
; #define PG8_LDA(dst, b, h) do { _Pragma("unroll") for (int m = 0; m < 4; ++m) _Pragma("unroll") for (int k = 0; k < 2; ++k) dst[m][k] = *(const LAS bf16x8*)(lds + PG8_SA(b, h) + aoff + m * 2048 + k * 1024); } while (0)
; #define PG8_LDB(dst, b, h) do { _Pragma("unroll") for (int n = 0; n < 2; ++n) _Pragma("unroll") for (int k = 0; k < 2; ++k) dst[n][k] = *(const LAS bf16x8*)(lds + PG8_SB(b, h) + boff + n * 2048 + k * 1024); } while (0)
; #define PG8_MMA(ai, bj, At, Bt) do { __builtin_amdgcn_s_setprio(1); _Pragma("unroll") for (int m = 0; m < 4; ++m) _Pragma("unroll") for (int n = 0; n < 2; ++n) _Pragma("unroll") for (int k = 0; k < 2; ++k) \
;         acc[ai][bj][m][n] = __builtin_amdgcn_mfma_f32_16x16x32_bf16(Bt[n][k], At[m][k], acc[ai][bj][m][n], 0, 0, 0); __builtin_amdgcn_s_setprio(0); } while (0)
; #define PG8_WAIT_V(n) asm volatile("s_waitcnt vmcnt(" #n ")" ::: "memory")
; #define PG8_WAIT_L(n) asm volatile("s_waitcnt lgkmcnt(" #n ")" ::: "memory")
; #define PG8_BAR __builtin_amdgcn_s_barrier()
; #define PG8_SCHED __builtin_amdgcn_sched_barrier(0)
; template <class Epi>
; DI void gemm_phase(LAS unsigned char* lds, const Gemm g, const StaticOrder& S, const Epi& E, const int tid) {
;     ...
;             PG8_LDB(B1, 0, 1); PG8_STAGE(PG8_SB(0, 0), b2, voffB);
;             PG8_BAR; PG8_WAIT_L(0); PG8_MMA(0, 1, At, B1); PG8_BAR;
;             PG8_LDA(At, 0, 1); PG8_STAGE(PG8_SA(0, 0), a2, voffA);
;             PG8_BAR; PG8_WAIT_L(0); PG8_MMA(1, 0, At, B0); PG8_BAR; PG8_SCHED;
;             PG8_STAGE(PG8_SB(0, 1), b2 + hstepB, voffB);
;             PG8_WAIT_V(6); PG8_BAR; PG8_MMA(1, 1, At, B1); PG8_BAR;
;             PG8_LDB(B0, 1, 0); PG8_SCHED; PG8_LDA(At, 1, 0); PG8_STAGE(PG8_SA(0, 1), a2 + hstepA, voffA);
;             PG8_WAIT_L(8); PG8_BAR; PG8_WAIT_L(0); PG8_MMA(0, 0, At, B0); PG8_BAR; PG8_SCHED;
	s_add_i32 s78, 0, 0x14000
	v_add_u32_e32 v152, s78, v150
	s_add_i32 s69, s69, s26
	ds_read_b128 v[214:217], v152
	ds_read_b128 v[218:221], v152 offset:1024
	ds_read_b128 v[222:225], v152 offset:2048
	ds_read_b128 v[226:229], v152 offset:3072
	v_lshl_add_u64 v[152:153], s[6:7], 0, v[0:1]
	s_mov_b32 m0, s69
	v_lshl_add_u64 v[170:171], s[6:7], 0, v[130:131]
	global_load_lds_dwordx4 v[152:153], off
	s_add_i32 m0, s69, 0x2000
	s_nop 0
	global_load_lds_dwordx4 v[170:171], off
	s_barrier
	s_waitcnt lgkmcnt(0)
	s_setprio 1
	s_waitcnt lgkmcnt(0)
	v_mfma_f32_16x16x32_bf16 v[110:113], v[214:217], v[182:185], v[110:113]
	v_mfma_f32_16x16x32_bf16 v[106:109], v[222:225], v[182:185], v[106:109]
	v_mfma_f32_16x16x32_bf16 v[94:97], v[214:217], v[190:193], v[94:97]
	v_mfma_f32_16x16x32_bf16 v[90:93], v[222:225], v[190:193], v[90:93]
	v_mfma_f32_16x16x32_bf16 v[78:81], v[214:217], v[198:201], v[78:81]
	v_mfma_f32_16x16x32_bf16 v[74:77], v[222:225], v[198:201], v[74:77]
	v_mfma_f32_16x16x32_bf16 v[70:73], v[214:217], v[206:209], v[70:73]
	v_mfma_f32_16x16x32_bf16 v[66:69], v[222:225], v[206:209], v[66:69]
	v_mfma_f32_16x16x32_bf16 v[110:113], v[218:221], v[186:189], v[110:113]
	v_mfma_f32_16x16x32_bf16 v[106:109], v[226:229], v[186:189], v[106:109]
	v_mfma_f32_16x16x32_bf16 v[94:97], v[218:221], v[194:197], v[94:97]
	v_mfma_f32_16x16x32_bf16 v[90:93], v[226:229], v[194:197], v[90:93]
	v_mfma_f32_16x16x32_bf16 v[78:81], v[218:221], v[202:205], v[78:81]
	v_mfma_f32_16x16x32_bf16 v[74:77], v[226:229], v[202:205], v[74:77]
	v_mfma_f32_16x16x32_bf16 v[70:73], v[218:221], v[210:213], v[70:73]
	v_mfma_f32_16x16x32_bf16 v[66:69], v[226:229], v[210:213], v[66:69]
	s_setprio 0
	s_mov_b32 m0, s41
	v_lshl_add_u64 v[230:231], s[50:51], 0, v[134:135]
	s_barrier
	ds_read_b128 v[182:185], v151 offset:16384
	ds_read_b128 v[186:189], v151 offset:17408
	ds_read_b128 v[190:193], v151 offset:18432
	ds_read_b128 v[194:197], v151 offset:19456
	ds_read_b128 v[198:201], v151 offset:20480
	ds_read_b128 v[202:205], v151 offset:21504
	ds_read_b128 v[206:209], v151 offset:22528
	ds_read_b128 v[210:213], v151 offset:23552
	global_load_lds_dwordx4 v[230:231], off
	v_lshl_add_u64 v[230:231], s[50:51], 0, v[132:133]
	s_mov_b32 m0, s55
	s_nop 0
	global_load_lds_dwordx4 v[230:231], off
	s_barrier
	s_waitcnt lgkmcnt(0)
	s_setprio 1
	s_waitcnt lgkmcnt(0)
	v_mfma_f32_16x16x32_bf16 v[62:65], v[158:161], v[182:185], v[62:65]
	v_mfma_f32_16x16x32_bf16 v[58:61], v[166:169], v[182:185], v[58:61]
	v_mfma_f32_16x16x32_bf16 v[54:57], v[158:161], v[190:193], v[54:57]
	v_mfma_f32_16x16x32_bf16 v[50:53], v[166:169], v[190:193], v[50:53]
	v_mfma_f32_16x16x32_bf16 v[38:41], v[158:161], v[198:201], v[38:41]
	v_mfma_f32_16x16x32_bf16 v[34:37], v[166:169], v[198:201], v[34:37]
	v_mfma_f32_16x16x32_bf16 v[22:25], v[158:161], v[206:209], v[22:25]
	v_mfma_f32_16x16x32_bf16 v[18:21], v[166:169], v[206:209], v[18:21]
	v_mfma_f32_16x16x32_bf16 v[62:65], v[162:165], v[186:189], v[62:65]
	v_mfma_f32_16x16x32_bf16 v[58:61], v[178:181], v[186:189], v[58:61]
	v_mfma_f32_16x16x32_bf16 v[54:57], v[162:165], v[194:197], v[54:57]
	v_mfma_f32_16x16x32_bf16 v[50:53], v[178:181], v[194:197], v[50:53]
	v_mfma_f32_16x16x32_bf16 v[38:41], v[162:165], v[202:205], v[38:41]
	v_mfma_f32_16x16x32_bf16 v[34:37], v[178:181], v[202:205], v[34:37]
	v_mfma_f32_16x16x32_bf16 v[22:25], v[162:165], v[210:213], v[22:25]
	v_mfma_f32_16x16x32_bf16 v[18:21], v[178:181], v[210:213], v[18:21]
	s_setprio 0
	s_barrier
	s_add_u32 s86, s6, 0x80000
	s_addc_u32 s87, s7, 0
	s_add_i32 s69, s78, s26
	v_lshl_add_u64 v[158:159], s[86:87], 0, v[0:1]
	s_mov_b32 m0, s69
	s_nop 0
	global_load_lds_dwordx4 v[158:159], off
	v_lshl_add_u64 v[158:159], s[86:87], 0, v[130:131]
	s_add_i32 m0, s69, 0x2000
	s_nop 0
	global_load_lds_dwordx4 v[158:159], off
	s_waitcnt vmcnt(6)
	s_barrier
	s_setprio 1
	v_mfma_f32_16x16x32_bf16 v[46:49], v[214:217], v[182:185], v[46:49]
	v_mfma_f32_16x16x32_bf16 v[42:45], v[222:225], v[182:185], v[42:45]
	v_mfma_f32_16x16x32_bf16 v[30:33], v[214:217], v[190:193], v[30:33]
	v_mfma_f32_16x16x32_bf16 v[26:29], v[222:225], v[190:193], v[26:29]
	v_mfma_f32_16x16x32_bf16 v[14:17], v[214:217], v[198:201], v[14:17]
	v_mfma_f32_16x16x32_bf16 v[10:13], v[222:225], v[198:201], v[10:13]
	v_mfma_f32_16x16x32_bf16 v[6:9], v[214:217], v[206:209], v[6:9]
	v_mfma_f32_16x16x32_bf16 v[2:5], v[222:225], v[206:209], v[2:5]
	v_mfma_f32_16x16x32_bf16 v[46:49], v[218:221], v[186:189], v[46:49]
	v_mfma_f32_16x16x32_bf16 v[42:45], v[226:229], v[186:189], v[42:45]
	v_mfma_f32_16x16x32_bf16 v[30:33], v[218:221], v[194:197], v[30:33]
	v_mfma_f32_16x16x32_bf16 v[26:29], v[226:229], v[194:197], v[26:29]
	v_mfma_f32_16x16x32_bf16 v[14:17], v[218:221], v[202:205], v[14:17]
	v_mfma_f32_16x16x32_bf16 v[10:13], v[226:229], v[202:205], v[10:13]
	v_mfma_f32_16x16x32_bf16 v[6:9], v[218:221], v[210:213], v[6:9]
	v_mfma_f32_16x16x32_bf16 v[2:5], v[226:229], v[210:213], v[2:5]
	s_setprio 0
	s_add_i32 s69, 0, 0x18000
	v_add_u32_e32 v173, s69, v150
	s_barrier
	ds_read_b128 v[158:161], v173
	ds_read_b128 v[162:165], v173 offset:1024
	ds_read_b128 v[166:169], v173 offset:2048
	ds_read_b128 v[178:181], v173 offset:3072
	s_add_u32 s50, s50, 0x80000
	s_addc_u32 s51, s51, 0
	s_mov_b32 m0, s56
	v_lshl_add_u64 v[214:215], s[50:51], 0, v[134:135]
	ds_read_b128 v[182:185], v151 offset:32768
	ds_read_b128 v[186:189], v151 offset:33792
	ds_read_b128 v[190:193], v151 offset:34816
	ds_read_b128 v[194:197], v151 offset:35840
	ds_read_b128 v[198:201], v151 offset:36864
	ds_read_b128 v[202:205], v151 offset:37888
	ds_read_b128 v[206:209], v151 offset:38912
	ds_read_b128 v[210:213], v151 offset:39936
	global_load_lds_dwordx4 v[214:215], off
	v_lshl_add_u64 v[214:215], s[50:51], 0, v[132:133]
	s_mov_b32 m0, s57
	s_nop 0
	global_load_lds_dwordx4 v[214:215], off
	s_waitcnt lgkmcnt(8)
	s_barrier
; #define PG8_STAGE(bufoff, gbase, voff) do { _Pragma("unroll") for (int _i = 0; _i < 2; ++_i) \
;         __builtin_amdgcn_global_load_lds((const unsigned*)((const char*)(gbase) + (voff)[_i]), (LAS unsigned*)(lds + (bufoff) + ldsw + _i * 8192), 16, 0, 0); } while (0)
; #define PG8_LDA(dst, b, h) do { _Pragma("unroll") for (int m = 0; m < 4; ++m) _Pragma("unroll") for (int k = 0; k < 2; ++k) dst[m][k] = *(const LAS bf16x8*)(lds + PG8_SA(b, h) + aoff + m * 2048 + k * 1024); } while (0)
; #define PG8_LDB(dst, b, h) do { _Pragma("unroll") for (int n = 0; n < 2; ++n) _Pragma("unroll") for (int k = 0; k < 2; ++k) dst[n][k] = *(const LAS bf16x8*)(lds + PG8_SB(b, h) + boff + n * 2048 + k * 1024); } while (0)
; #define PG8_MMA(ai, bj, At, Bt) do { __builtin_amdgcn_s_setprio(1); _Pragma("unroll") for (int m = 0; m < 4; ++m) _Pragma("unroll") for (int n = 0; n < 2; ++n) _Pragma("unroll") for (int k = 0; k < 2; ++k) \
;         acc[ai][bj][m][n] = __builtin_amdgcn_mfma_f32_16x16x32_bf16(Bt[n][k], At[m][k], acc[ai][bj][m][n], 0, 0, 0); __builtin_amdgcn_s_setprio(0); } while (0)
; #define PG8_WAIT_V(n) asm volatile("s_waitcnt vmcnt(" #n ")" ::: "memory")
; #define PG8_WAIT_L(n) asm volatile("s_waitcnt lgkmcnt(" #n ")" ::: "memory")
; #define PG8_BAR __builtin_amdgcn_s_barrier()
; #define PG8_SCHED __builtin_amdgcn_sched_barrier(0)
; template <class Epi>
; DI void gemm_phase(LAS unsigned char* lds, const Gemm g, const StaticOrder& S, const Epi& E, const int tid) {
;     ...
;             PG8_WAIT_L(8); PG8_BAR; PG8_WAIT_L(0); PG8_MMA(0, 0, At, B0); PG8_BAR; PG8_SCHED;
;             PG8_LDB(B1, 1, 1); PG8_STAGE(PG8_SB(1, 0), b3, voffB);
;             PG8_BAR; PG8_WAIT_L(0); PG8_MMA(0, 1, At, B1); PG8_BAR;
;             PG8_LDA(At, 1, 1); PG8_STAGE(PG8_SA(1, 0), a3, voffA);
;             PG8_BAR; PG8_WAIT_L(0); PG8_MMA(1, 0, At, B0); PG8_BAR; PG8_SCHED;
;             PG8_STAGE(PG8_SB(1, 1), b3 + hstepB, voffB);
;             PG8_WAIT_V(6); PG8_BAR; PG8_MMA(1, 1, At, B1); PG8_BAR;
	s_waitcnt lgkmcnt(0)
	s_setprio 1
	s_waitcnt lgkmcnt(0)
	v_mfma_f32_16x16x32_bf16 v[126:129], v[158:161], v[182:185], v[126:129]
	v_mfma_f32_16x16x32_bf16 v[122:125], v[166:169], v[182:185], v[122:125]
	v_mfma_f32_16x16x32_bf16 v[118:121], v[158:161], v[190:193], v[118:121]
	v_mfma_f32_16x16x32_bf16 v[114:117], v[166:169], v[190:193], v[114:117]
	v_mfma_f32_16x16x32_bf16 v[102:105], v[158:161], v[198:201], v[102:105]
	v_mfma_f32_16x16x32_bf16 v[98:101], v[166:169], v[198:201], v[98:101]
	v_mfma_f32_16x16x32_bf16 v[86:89], v[158:161], v[206:209], v[86:89]
	v_mfma_f32_16x16x32_bf16 v[82:85], v[166:169], v[206:209], v[82:85]
	v_mfma_f32_16x16x32_bf16 v[126:129], v[162:165], v[186:189], v[126:129]
	v_mfma_f32_16x16x32_bf16 v[122:125], v[178:181], v[186:189], v[122:125]
	v_mfma_f32_16x16x32_bf16 v[118:121], v[162:165], v[194:197], v[118:121]
	v_mfma_f32_16x16x32_bf16 v[114:117], v[178:181], v[194:197], v[114:117]
	v_mfma_f32_16x16x32_bf16 v[102:105], v[162:165], v[202:205], v[102:105]
	v_mfma_f32_16x16x32_bf16 v[98:101], v[178:181], v[202:205], v[98:101]
	v_mfma_f32_16x16x32_bf16 v[86:89], v[162:165], v[210:213], v[86:89]
	v_mfma_f32_16x16x32_bf16 v[82:85], v[178:181], v[210:213], v[82:85]
	s_setprio 0
	s_barrier
	s_add_i32 s50, 0, 0x1c000
	s_add_i32 s51, s69, s26
	v_add_u32_e32 v173, s50, v150
	v_lshl_add_u64 v[152:153], v[152:153], 0, s[84:85]
	s_mov_b32 m0, s51
	ds_read_b128 v[214:217], v173
	ds_read_b128 v[218:221], v173 offset:1024
	ds_read_b128 v[222:225], v173 offset:2048
	ds_read_b128 v[226:229], v173 offset:3072
	global_load_lds_dwordx4 v[152:153], off
	v_lshl_add_u64 v[152:153], v[170:171], 0, s[84:85]
	s_add_i32 m0, s51, 0x2000
	s_nop 0
	global_load_lds_dwordx4 v[152:153], off
	s_barrier
	s_waitcnt lgkmcnt(0)
	s_setprio 1
	s_waitcnt lgkmcnt(0)
	v_mfma_f32_16x16x32_bf16 v[110:113], v[214:217], v[182:185], v[110:113]
	v_mfma_f32_16x16x32_bf16 v[106:109], v[222:225], v[182:185], v[106:109]
	v_mfma_f32_16x16x32_bf16 v[94:97], v[214:217], v[190:193], v[94:97]
	v_mfma_f32_16x16x32_bf16 v[90:93], v[222:225], v[190:193], v[90:93]
	v_mfma_f32_16x16x32_bf16 v[78:81], v[214:217], v[198:201], v[78:81]
	v_mfma_f32_16x16x32_bf16 v[74:77], v[222:225], v[198:201], v[74:77]
	v_mfma_f32_16x16x32_bf16 v[70:73], v[214:217], v[206:209], v[70:73]
	v_mfma_f32_16x16x32_bf16 v[66:69], v[222:225], v[206:209], v[66:69]
	v_mfma_f32_16x16x32_bf16 v[110:113], v[218:221], v[186:189], v[110:113]
	v_mfma_f32_16x16x32_bf16 v[106:109], v[226:229], v[186:189], v[106:109]
	v_mfma_f32_16x16x32_bf16 v[94:97], v[218:221], v[194:197], v[94:97]
	v_mfma_f32_16x16x32_bf16 v[90:93], v[226:229], v[194:197], v[90:93]
	v_mfma_f32_16x16x32_bf16 v[78:81], v[218:221], v[202:205], v[78:81]
	v_mfma_f32_16x16x32_bf16 v[74:77], v[226:229], v[202:205], v[74:77]
	v_mfma_f32_16x16x32_bf16 v[70:73], v[218:221], v[210:213], v[70:73]
	v_mfma_f32_16x16x32_bf16 v[66:69], v[226:229], v[210:213], v[66:69]
	s_setprio 0
	s_mov_b32 m0, s59
	v_lshl_add_u64 v[152:153], s[8:9], 0, v[134:135]
	s_barrier
	ds_read_b128 v[182:185], v151 offset:49152
	ds_read_b128 v[186:189], v151 offset:50176
	ds_read_b128 v[190:193], v151 offset:51200
	ds_read_b128 v[194:197], v151 offset:52224
	ds_read_b128 v[198:201], v151 offset:53248
	ds_read_b128 v[202:205], v151 offset:54272
	ds_read_b128 v[206:209], v151 offset:55296
	ds_read_b128 v[210:213], v151 offset:56320
	global_load_lds_dwordx4 v[152:153], off
	v_lshl_add_u64 v[152:153], s[8:9], 0, v[132:133]
	s_mov_b32 m0, s60
	s_nop 0
	global_load_lds_dwordx4 v[152:153], off
	s_barrier
	s_waitcnt lgkmcnt(0)
	s_setprio 1
	s_waitcnt lgkmcnt(0)
	v_mfma_f32_16x16x32_bf16 v[62:65], v[158:161], v[182:185], v[62:65]
	v_mfma_f32_16x16x32_bf16 v[58:61], v[166:169], v[182:185], v[58:61]
	v_mfma_f32_16x16x32_bf16 v[54:57], v[158:161], v[190:193], v[54:57]
	v_mfma_f32_16x16x32_bf16 v[50:53], v[166:169], v[190:193], v[50:53]
	v_mfma_f32_16x16x32_bf16 v[38:41], v[158:161], v[198:201], v[38:41]
	v_mfma_f32_16x16x32_bf16 v[34:37], v[166:169], v[198:201], v[34:37]
	v_mfma_f32_16x16x32_bf16 v[22:25], v[158:161], v[206:209], v[22:25]
	v_mfma_f32_16x16x32_bf16 v[18:21], v[166:169], v[206:209], v[18:21]
	v_mfma_f32_16x16x32_bf16 v[62:65], v[162:165], v[186:189], v[62:65]
	v_mfma_f32_16x16x32_bf16 v[58:61], v[178:181], v[186:189], v[58:61]
	v_mfma_f32_16x16x32_bf16 v[54:57], v[162:165], v[194:197], v[54:57]
	v_mfma_f32_16x16x32_bf16 v[50:53], v[178:181], v[194:197], v[50:53]
	v_mfma_f32_16x16x32_bf16 v[38:41], v[162:165], v[202:205], v[38:41]
	v_mfma_f32_16x16x32_bf16 v[34:37], v[178:181], v[202:205], v[34:37]
	v_mfma_f32_16x16x32_bf16 v[22:25], v[162:165], v[210:213], v[22:25]
	v_mfma_f32_16x16x32_bf16 v[18:21], v[178:181], v[210:213], v[18:21]
	s_setprio 0
	s_barrier
	s_add_u32 s6, s6, 0x80080
	s_addc_u32 s7, s7, 0
	s_add_i32 s8, s50, s26
	v_lshl_add_u64 v[152:153], s[6:7], 0, v[0:1]
	s_mov_b32 m0, s8
	s_nop 0
	global_load_lds_dwordx4 v[152:153], off
	v_lshl_add_u64 v[152:153], s[6:7], 0, v[130:131]
	s_add_i32 m0, s8, 0x2000
	s_nop 0
	global_load_lds_dwordx4 v[152:153], off
	s_waitcnt vmcnt(6)
	s_barrier
; DI unsigned pk2(float a, float b) { f32x2 v = {a, b}; bf16v2 r = __builtin_convertvector(v, bf16v2); return __builtin_bit_cast(unsigned, r); }
;     DI void operator()(const f32x4 (&acc)[2][2][4][2], const Unit& u, int wr, int wc, int fr, int fq) const {
;         if (nt) {
;             unsigned char* tb = (unsigned char*)O + ((size_t)(u.pm * nt + u.pn) << 17) + (wr * 4 + wc) * 1024 + (fq * 16 + fr) * 16;
; #pragma unroll
;             for (int ai = 0; ai < 2; ++ai)
; #pragma unroll
;                 for (int m = 0; m < 4; ++m)
; #pragma unroll
;                     for (int bj = 0; bj < 2; ++bj) { const f32x4 v0 = acc[ai][bj][m][0], v1 = acc[ai][bj][m][1];
;                         u32x4 w; w.x = pk2(v0[0], v0[1]); w.y = pk2(v0[2], v0[3]); w.z = pk2(v1[0], v1[1]); w.w = pk2(v1[2], v1[3]);
;                         *(u32x4*)(tb + ((ai * 4 + m) * 2 + bj) * 8192) = w; }
;             return;
; template <class Epi>
; DI void gemm_phase(LAS unsigned char* lds, const Gemm g, const StaticOrder& S, const Epi& E, const int tid) {
;     ...
;             const bool last = (t == nt - 2);
;             const char* a1 = cA + PG8_KTA(t + 1);
;             const char* a2 = last ? nA : cA + PG8_KTA(t + 2); const char* b2 = last ? nB : cB + (size_t)(t + 2) * kstep;
;             const char* a3 = last ? nA + PG8_KTA(1) : cA + PG8_KTA(t + 3); const char* b3 = b2 + kstep;
	s_setprio 1
	v_mfma_f32_16x16x32_bf16 v[46:49], v[214:217], v[182:185], v[46:49]
	v_mfma_f32_16x16x32_bf16 v[42:45], v[222:225], v[182:185], v[42:45]
	v_mfma_f32_16x16x32_bf16 v[30:33], v[214:217], v[190:193], v[30:33]
	v_mfma_f32_16x16x32_bf16 v[26:29], v[222:225], v[190:193], v[26:29]
	v_mfma_f32_16x16x32_bf16 v[14:17], v[214:217], v[198:201], v[14:17]
	v_mfma_f32_16x16x32_bf16 v[10:13], v[222:225], v[198:201], v[10:13]
	v_mfma_f32_16x16x32_bf16 v[6:9], v[214:217], v[206:209], v[6:9]
	v_mfma_f32_16x16x32_bf16 v[2:5], v[222:225], v[206:209], v[2:5]
	v_mfma_f32_16x16x32_bf16 v[46:49], v[218:221], v[186:189], v[46:49]
	v_mfma_f32_16x16x32_bf16 v[42:45], v[226:229], v[186:189], v[42:45]
	v_mfma_f32_16x16x32_bf16 v[30:33], v[218:221], v[194:197], v[30:33]
	v_mfma_f32_16x16x32_bf16 v[26:29], v[226:229], v[194:197], v[26:29]
	v_mfma_f32_16x16x32_bf16 v[14:17], v[218:221], v[202:205], v[14:17]
	v_mfma_f32_16x16x32_bf16 v[10:13], v[226:229], v[202:205], v[10:13]
	v_mfma_f32_16x16x32_bf16 v[6:9], v[218:221], v[210:213], v[6:9]
	v_mfma_f32_16x16x32_bf16 v[2:5], v[226:229], v[210:213], v[2:5]
	s_setprio 0
	s_add_i32 s68, s68, 2
	s_add_u32 s4, s4, 0x100
	s_addc_u32 s5, s5, 0
	s_add_u32 s6, s44, s4
	s_addc_u32 s7, s45, s5
	s_add_u32 s8, s6, 0x100
	s_addc_u32 s9, s7, 0
	s_add_u32 s69, s66, s4
	s_addc_u32 s78, s67, s5
	s_add_u32 s86, s6, 0x180
	s_addc_u32 s87, s7, 0
	s_cmpk_eq_i32 s4, 0xf00
	s_cselect_b32 s51, s30, s9
	s_cselect_b32 s50, s31, s8
	s_cselect_b32 s7, s39, s78
	s_cselect_b32 s6, s43, s69
	s_cselect_b32 s9, s65, s87
	s_cselect_b32 s8, s64, s86
	s_cmp_gt_u32 s68, 29
	s_barrier
	s_cbranch_scc0 .LBB0_62
	s_mul_i32 s4, s40, s58
	s_add_i32 s4, s4, s63
	s_ashr_i32 s5, s4, 31
	s_lshl_b64 s[4:5], s[4:5], 17
	v_lshl_add_u64 v[144:145], v[136:137], 0, s[4:5]
	s_movk_i32 s4, 0x2000
	v_cvt_pk_bf16_f32 v110, v110, v111
	v_cvt_pk_bf16_f32 v111, v112, v113
	v_cvt_pk_bf16_f32 v112, v106, v107
	v_add_co_u32_e32 v106, vcc, s4, v144
	v_cvt_pk_bf16_f32 v113, v108, v109
	s_nop 0
	v_addc_co_u32_e32 v107, vcc, 0, v145, vcc
	global_store_dwordx4 v[106:107], v[110:113], off
	s_movk_i32 s4, 0x6000
	v_cvt_pk_bf16_f32 v94, v94, v95
	v_add_co_u32_e32 v110, vcc, s3, v144
	v_cvt_pk_bf16_f32 v95, v96, v97
	s_nop 0
	v_addc_co_u32_e32 v111, vcc, 0, v145, vcc
	v_cvt_pk_bf16_f32 v96, v90, v91
	v_add_co_u32_e32 v90, vcc, s4, v144
	v_cvt_pk_bf16_f32 v97, v92, v93
	s_nop 0
	v_addc_co_u32_e32 v91, vcc, 0, v145, vcc
	s_mov_b32 s4, 0x8000
	global_store_dwordx4 v[90:91], v[94:97], off
	v_cvt_pk_bf16_f32 v78, v78, v79
	v_cvt_pk_bf16_f32 v79, v80, v81
	v_add_co_u32_e32 v94, vcc, s4, v144
	s_mov_b32 s4, 0xa000
	s_nop 0
	v_addc_co_u32_e32 v95, vcc, 0, v145, vcc
	v_cvt_pk_bf16_f32 v80, v74, v75
	v_add_co_u32_e32 v74, vcc, s4, v144
	v_cvt_pk_bf16_f32 v81, v76, v77
	s_nop 0
	v_addc_co_u32_e32 v75, vcc, 0, v145, vcc
	global_store_dwordx4 v[74:75], v[78:81], off
	s_mov_b32 s4, 0xe000
	v_cvt_pk_bf16_f32 v70, v70, v71
	v_add_co_u32_e32 v78, vcc, s13, v144
	v_cvt_pk_bf16_f32 v71, v72, v73
	s_nop 0
	v_addc_co_u32_e32 v79, vcc, 0, v145, vcc
	v_cvt_pk_bf16_f32 v72, v66, v67
	v_add_co_u32_e32 v66, vcc, s4, v144
	s_mov_b32 s4, 0x10000
	s_nop 0
	v_addc_co_u32_e32 v67, vcc, 0, v145, vcc
	v_cvt_pk_bf16_f32 v62, v62, v63
	v_cvt_pk_bf16_f32 v63, v64, v65
	v_cvt_pk_bf16_f32 v64, v58, v59
	v_add_co_u32_e32 v58, vcc, s4, v144
	s_mov_b32 s4, 0x12000
	s_nop 0
	v_addc_co_u32_e32 v59, vcc, 0, v145, vcc
	v_cvt_pk_bf16_f32 v46, v46, v47
	v_cvt_pk_bf16_f32 v47, v48, v49
	v_cvt_pk_bf16_f32 v48, v42, v43
	v_add_co_u32_e32 v42, vcc, s4, v144
	v_cvt_pk_bf16_f32 v49, v44, v45
	s_nop 0
	v_addc_co_u32_e32 v43, vcc, 0, v145, vcc
	s_mov_b32 s4, 0x14000
	global_store_dwordx4 v[42:43], v[46:49], off
	v_cvt_pk_bf16_f32 v30, v30, v31
	v_cvt_pk_bf16_f32 v31, v32, v33
	v_add_co_u32_e32 v46, vcc, s4, v144
	s_mov_b32 s4, 0x16000
	s_nop 0
	v_addc_co_u32_e32 v47, vcc, 0, v145, vcc
	v_cvt_pk_bf16_f32 v32, v26, v27
	v_add_co_u32_e32 v26, vcc, s4, v144
	v_cvt_pk_bf16_f32 v33, v28, v29
	s_nop 0
	v_addc_co_u32_e32 v27, vcc, 0, v145, vcc
	s_mov_b32 s4, 0x18000
	global_store_dwordx4 v[26:27], v[30:33], off
	v_cvt_pk_bf16_f32 v14, v14, v15
	v_cvt_pk_bf16_f32 v15, v16, v17
	v_add_co_u32_e32 v30, vcc, s4, v144
	s_mov_b32 s4, 0x1a000
	s_nop 0
	v_addc_co_u32_e32 v31, vcc, 0, v145, vcc
	v_cvt_pk_bf16_f32 v16, v10, v11
	v_add_co_u32_e32 v10, vcc, s4, v144
	v_cvt_pk_bf16_f32 v17, v12, v13
	s_nop 0
	v_addc_co_u32_e32 v11, vcc, 0, v145, vcc
	s_mov_b32 s4, 0x1c000
	global_store_dwordx4 v[10:11], v[14:17], off
	v_cvt_pk_bf16_f32 v6, v6, v7
	v_cvt_pk_bf16_f32 v7, v8, v9
	v_add_co_u32_e32 v14, vcc, s4, v144
	v_cvt_pk_bf16_f32 v8, v2, v3
	s_nop 0
	v_addc_co_u32_e32 v15, vcc, 0, v145, vcc
	v_add_co_u32_e32 v2, vcc, 0x1e000, v144
	v_cvt_pk_bf16_f32 v126, v126, v127
	s_nop 0
	v_addc_co_u32_e32 v3, vcc, 0, v145, vcc
	v_cvt_pk_bf16_f32 v127, v128, v129
	v_cvt_pk_bf16_f32 v128, v122, v123
	v_cvt_pk_bf16_f32 v129, v124, v125
	v_cvt_pk_bf16_f32 v106, v118, v119
	v_cvt_pk_bf16_f32 v107, v120, v121
	v_cvt_pk_bf16_f32 v108, v114, v115
	v_cvt_pk_bf16_f32 v109, v116, v117
	v_cvt_pk_bf16_f32 v90, v102, v103
	v_cvt_pk_bf16_f32 v91, v104, v105
	v_cvt_pk_bf16_f32 v92, v98, v99
	v_cvt_pk_bf16_f32 v93, v100, v101
	v_cvt_pk_bf16_f32 v74, v86, v87
	v_cvt_pk_bf16_f32 v75, v88, v89
	v_cvt_pk_bf16_f32 v76, v82, v83
	v_cvt_pk_bf16_f32 v77, v84, v85
	v_cvt_pk_bf16_f32 v73, v68, v69
	v_cvt_pk_bf16_f32 v65, v60, v61
	v_cvt_pk_bf16_f32 v42, v54, v55
	v_cvt_pk_bf16_f32 v43, v56, v57
	v_cvt_pk_bf16_f32 v44, v50, v51
	v_cvt_pk_bf16_f32 v45, v52, v53
	v_cvt_pk_bf16_f32 v26, v38, v39
	v_cvt_pk_bf16_f32 v27, v40, v41
	v_cvt_pk_bf16_f32 v28, v34, v35
	v_cvt_pk_bf16_f32 v29, v36, v37
	v_cvt_pk_bf16_f32 v10, v22, v23
	v_cvt_pk_bf16_f32 v11, v24, v25
	v_cvt_pk_bf16_f32 v12, v18, v19
	v_cvt_pk_bf16_f32 v13, v20, v21
	v_cvt_pk_bf16_f32 v9, v4, v5
	s_and_b64 vcc, exec, s[34:35]
	s_mov_b32 s63, s38
	s_mov_b32 s40, s42
	s_mov_b64 s[4:5], s[48:49]
	s_mov_b64 s[44:45], s[46:47]
	global_store_dwordx4 v[144:145], v[126:129], off
	global_store_dwordx4 v[110:111], v[106:109], off
	global_store_dwordx4 v[94:95], v[90:93], off
	global_store_dwordx4 v[78:79], v[74:77], off
	global_store_dwordx4 v[66:67], v[70:73], off
	global_store_dwordx4 v[58:59], v[62:65], off
	global_store_dwordx4 v[46:47], v[42:45], off
	global_store_dwordx4 v[30:31], v[26:29], off
	global_store_dwordx4 v[14:15], v[10:13], off
	global_store_dwordx4 v[2:3], v[6:9], off
	s_cbranch_vccz .LBB0_59
	s_waitcnt vmcnt(0)
	s_cmpk_gt_u32 s25, 0xff
	s_cbranch_scc1 .LBB0_66
	s_barrier
